# v9 plus stacked latency de-serialisation: gMLP w_s loads issued together, D1 conv row-load drains removed, residual epilogue store-ack waits removed, conv tap LDS table padded
# speedup vs baseline: 1.0359x; 1.0148x over previous
; #define INP(i) (*(const float* const __attribute__((address_space(4)))*)(ka_base() + 8 * (i)))
; __global__ void __launch_bounds__(NTHREADS, 2) fwd_megakernel(Params p) {
;     ...
;             if (tidx < 384) { const int X = tidx >> 7, d = tidx & 127; ((f32x4*)(lds + 139264))[tidx] = *(const f32x4*)(INP(10) + ((size_t)l * 3072 + X * 1024 + 128 * (bid & 7) + d) * 4); }
.LBB0_100:
	s_and_b64 vcc, exec, s[48:49]
	s_cbranch_vccz .LBB0_666
	v_readlane_b32 s0, v254, 44
	s_cmp_gt_i32 s0, 1
	s_mov_b64 s[0:1], -1
	s_cbranch_scc0 .LBB0_664
	s_movk_i32 s0, 0x180
	v_cmp_gt_i32_e32 vcc, s0, v252
	s_and_saveexec_b64 s[2:3], vcc
	s_cbranch_execz .LBB0_104
	v_lshlrev_b32_e32 v0, 3, v252
	v_and_b32_e32 v0, 0xfffffc00, v0
	s_load_dwordx2 s[0:1], s[76:77], 0x50
	v_ashrrev_i32_e32 v1, 31, v0
	v_mov_b32_e32 v2, 0xc00
	v_mad_u64_u32 v[0:1], s[4:5], s80, v2, v[0:1]
	v_readlane_b32 s4, v253, 21
	s_waitcnt lgkmcnt(0)
	v_lshl_add_u32 v4, v252, 4, 0
	v_add_u32_e32 v4, 0x22000, v4
	v_lshrrev_b32_e32 v5, 4, v252
	v_lshl_add_u32 v4, v5, 4, v4
	v_or_b32_e32 v0, s4, v0
	s_movk_i32 s4, 0x7f
	v_and_or_b32 v0, v252, s4, v0
	s_waitcnt lgkmcnt(0)
	v_lshl_add_u64 v[0:1], v[0:1], 4, s[0:1]
	global_load_dwordx4 v[0:3], v[0:1], off
	s_waitcnt vmcnt(0)
	ds_write_b128 v4, v[0:3]

; #define INP(i) (*(const float* const __attribute__((address_space(4)))*)(ka_base() + 8 * (i)))
; __device__ __forceinline__ unsigned cvt_pk_bf16(float lo, float hi) { const f32x2 v = {lo, hi}; const bf16v2_t b = __builtin_convertvector(v, bf16v2_t); return __builtin_bit_cast(unsigned, b); }
; __device__ __forceinline__ void gmlp_unit(const Params& p, int g, int l, int ci, unsigned char* lds, const int tidx) {
;     ...
;         { const float* ws = INP(8) + ((size_t)l * 8 + grp) * 16384; const int t = tid >> 2, s0 = 32 * (tid & 3);
; #pragma unroll
;           for (int k = 0; k < 4; ++k) {
;               f32x4 a = (f32x4){0.f, 0.f, 0.f, 0.f}, b = a;
;               if (t < nvalid && s0 + 8 * k <= t) { a = *(const f32x4*)(ws + t * 128 + s0 + 8 * k); b = *(const f32x4*)(ws + t * 128 + s0 + 8 * k + 4); }
;               float v[8] = {a[0], a[1], a[2], a[3], b[0], b[1], b[2], b[3]};
; #pragma unroll
;               for (int i = 0; i < 8; ++i) if (s0 + 8 * k + i > t) v[i] = 0.f;
;               u32x4 w; w.x = cvt_pk_bf16(v[0], v[1]); w.y = cvt_pk_bf16(v[2], v[3]); w.z = cvt_pk_bf16(v[4], v[5]); w.w = cvt_pk_bf16(v[6], v[7]);
;               *(u32x4*)(sWs + t * 136 + s0 + 8 * k) = w;
;           } }
.LBB0_121:
	s_or_b64 exec, exec, s[0:1]
	v_mov_b32_e32 v100, 0
	v_mov_b32_e32 v101, 0
	v_mov_b32_e32 v102, 0
	v_mov_b32_e32 v103, 0
	v_mov_b32_e32 v104, 0
	v_mov_b32_e32 v105, 0
	v_mov_b32_e32 v106, 0
	v_mov_b32_e32 v107, 0
	v_mov_b32_e32 v108, 0
	v_mov_b32_e32 v109, 0
	v_mov_b32_e32 v110, 0
	v_mov_b32_e32 v111, 0
	v_mov_b32_e32 v112, 0
	v_mov_b32_e32 v113, 0
	v_mov_b32_e32 v114, 0
	v_mov_b32_e32 v115, 0
	s_and_saveexec_b64 s[0:1], s[20:21]
	s_cbranch_execz .LBB0_123
	global_load_dwordx4 v[100:103], v[12:13], off offset:48
	global_load_dwordx4 v[104:107], v[12:13], off offset:32
.LBB0_123:
	s_or_b64 exec, exec, s[0:1]
	s_and_saveexec_b64 s[0:1], s[24:25]
	s_cbranch_execz .LBB0_125
	global_load_dwordx4 v[108:111], v[12:13], off offset:80
	global_load_dwordx4 v[112:115], v[12:13], off offset:64
.LBB0_125:
	s_or_b64 exec, exec, s[0:1]
	v_readlane_b32 s0, v254, 54
	s_waitcnt vmcnt(0)
	v_cndmask_b32_e64 v1, v6, 0, s[38:39]
	v_readlane_b32 s1, v254, 55
	v_cndmask_b32_e64 v7, 0, v7, s[36:37]
	v_cndmask_b32_e64 v1, v1, v6, s[36:37]
	v_cndmask_b32_e64 v6, v8, 0, s[0:1]
	v_cndmask_b32_e64 v8, v9, 0, s[40:41]
	v_cndmask_b32_e64 v9, v2, 0, s[42:43]
	v_cndmask_b32_e64 v10, v3, 0, s[44:45]
	v_cndmask_b32_e64 v11, v4, 0, s[46:47]
	v_cndmask_b32_e64 v5, v5, 0, s[48:49]
	v_cvt_pk_bf16_f32 v2, v1, v7
	v_cvt_pk_bf16_f32 v3, v6, v8
	v_cvt_pk_bf16_f32 v4, v9, v10
	v_cvt_pk_bf16_f32 v5, v11, v5
	ds_write_b128 v53, v[2:5] offset:34816
	v_cndmask_b32_e64 v5, v104, 0, s[50:51]
	v_cndmask_b32_e64 v6, v105, 0, s[52:53]
	v_cndmask_b32_e64 v7, v106, 0, s[54:55]
	v_cndmask_b32_e64 v8, v107, 0, s[56:57]
	v_cndmask_b32_e64 v9, v100, 0, s[58:59]
	v_cndmask_b32_e64 v10, v101, 0, s[60:61]
	v_cndmask_b32_e64 v11, v102, 0, s[62:63]
	v_cndmask_b32_e64 v3, v103, 0, s[64:65]
	v_cvt_pk_bf16_f32 v0, v5, v6
	v_cvt_pk_bf16_f32 v1, v7, v8
	v_cvt_pk_bf16_f32 v2, v9, v10
	v_cvt_pk_bf16_f32 v3, v11, v3
	v_mov_b32_e32 v4, 0
	ds_write_b128 v53, v[0:3] offset:34832
	v_cndmask_b32_e64 v5, v112, 0, s[66:67]
	v_cndmask_b32_e64 v6, v113, 0, s[68:69]
	v_cndmask_b32_e64 v7, v114, 0, s[70:71]
	v_cndmask_b32_e64 v8, v115, 0, s[72:73]
	v_cndmask_b32_e64 v9, v108, 0, s[74:75]
	v_cndmask_b32_e64 v10, v109, 0, s[76:77]
	v_cndmask_b32_e64 v11, v110, 0, s[78:79]
	v_cndmask_b32_e64 v3, v111, 0, s[80:81]
	v_cvt_pk_bf16_f32 v0, v5, v6
	v_cvt_pk_bf16_f32 v1, v7, v8
	v_cvt_pk_bf16_f32 v2, v9, v10
	v_cvt_pk_bf16_f32 v3, v11, v3
	v_mov_b32_e32 v5, 0
	v_mov_b32_e32 v6, 0
	v_mov_b32_e32 v7, 0
	v_mov_b32_e32 v8, 0
	v_mov_b32_e32 v9, 0
	v_mov_b32_e32 v10, 0
	v_mov_b32_e32 v11, 0
	ds_write_b128 v53, v[0:3] offset:34848
	s_and_saveexec_b64 s[0:1], s[26:27]
	s_cbranch_execz .LBB0_127
	global_load_dwordx4 v[4:7], v[12:13], off offset:112
	global_load_dwordx4 v[8:11], v[12:13], off offset:96

; #define WSP() (*(unsigned char* const __attribute__((address_space(4)))*)(ka_base() + 8 * 22))
; __device__ __forceinline__ void d1_unit(const Params& p, int g, int l, int unit0, int nd1, unsigned char* lds0, const int tidx) {
;     const int half = __builtin_amdgcn_readfirstlane(tidx >> 8), tid = tidx & 255, wid = __builtin_amdgcn_readfirstlane((tidx >> 6) & 3), lane = tidx & 63, fr = lane & 15, fq = lane >> 4;
;     const int unit_raw = unit0 + half * (int)gridDim.x;
;     const bool active = unit_raw < nd1;
;     const int unit = active ? unit_raw : unit0;
;     unsigned char* lds = lds0 + half * 69632;
;     bf16_t* ACT = (bf16_t*)(WSP() + WS_ACT);
;     bf16_t* Qb = ACT + 2 * SLOT_EL; bf16_t* Kb = ACT + 3 * SLOT_EL; bf16_t* Vb = ACT + 4 * SLOT_EL;
;     bf16_t* KGT = (bf16_t*)(WSP() + WS_KGT) + (size_t)unit * 8192;
;     bf16_t* Pm = (bf16_t*)(WSP() + WS_P) + (size_t)unit * 4096;
;     const bf16_t* HALO = (const bf16_t*)(WSP() + WS_HALO);
;     const float* BG = (const float*)(WSP() + WS_BG); float* GL = (float*)(WSP() + WS_GL);
;     bf16_t* sq = (bf16_t*)lds; bf16_t* sk = sq + 64 * 136; bf16_t* sv = sk + 64 * 136;
;     float* Am = (float*)(lds + 52224);
;     float* sGam = (float*)(lds + 68608); float* sBeta = sGam + 64;
;     const int cid = unit >> 3, h = unit & 7;
;     const bool smp = cid >= 512; const int sb = cid - 512;
;     const int row0 = smp ? 32768 + 16 * sb : 64 * cid, nvalid = smp ? 16 : 64;
;     const int nloc = smp ? 0 : (cid & 63);
;     if (active) for (int pass = 0; pass < 2; ++pass) { const int c = (tid >> 3) + 32 * pass, sub = tid & 7, d0 = 16 * sub;
.LBB0_227:
	v_readlane_b32 s0, v254, 39
	v_readlane_b32 s1, v254, 40
	s_and_b64 s[0:1], s[0:1], exec
	s_movk_i32 s0, 0x1040
	s_cselect_b32 s18, s0, 0x1000
	v_readlane_b32 s0, v253, 0
	v_readlane_b32 s76, v254, 34
	v_readlane_b32 s80, v254, 52
	s_cmp_ge_i32 s0, s18
	v_readlane_b32 s77, v254, 35
	s_movk_i32 s75, 0x110
	v_readlane_b32 s81, v254, 53
	s_cbranch_scc1 .LBB0_663
	v_bfe_u32 v0, v252, 4, 2
	v_lshlrev_b32_e32 v1, 4, v252
	v_and_b32_e32 v131, 15, v252
	v_and_b32_e32 v130, 0x70, v1
	v_lshlrev_b32_e32 v132, 2, v0
	v_lshlrev_b32_e32 v1, 3, v0
	v_mov_b32_e32 v0, 0x2200
	v_mad_u32_u24 v166, v131, s75, v0
	v_mov_b32_e32 v0, 0x3300
	v_bfe_u32 v184, v252, 1, 7
	v_and_b32_e32 v129, 63, v252
	s_add_i32 s0, 0, 0x22000
	v_mad_u32_u24 v177, v131, s75, v0
	v_bfe_u32 v182, v252, 2, 6
	v_and_b32_e32 v134, 32, v33
	v_lshlrev_b32_e32 v0, 6, v184
	v_bfe_u32 v133, v252, 3, 5
	s_lshl_b64 s[12:13], s[80:81], 3
	v_mad_u32_u24 v135, v130, 17, s0
	v_cmp_eq_u32_e64 s[36:37], 0, v129
	v_cmp_gt_u32_e64 s[38:39], 2, v129
	v_cmp_gt_u32_e64 s[40:41], 4, v129
	v_cmp_gt_u32_e64 s[42:43], 8, v129
	v_cmp_gt_u32_e64 s[44:45], 16, v129
	v_cmp_gt_u32_e64 s[46:47], 32, v129
	v_cmp_eq_u32_e64 s[48:49], 63, v129
	v_mul_u32_u24_e32 v141, 0x110, v131
	v_or_b32_e32 v149, 1, v132
	v_or_b32_e32 v155, 2, v132
	v_or_b32_e32 v164, 3, v132
	v_or_b32_e32 v165, 32, v131
	v_or_b32_e32 v167, 16, v132
	v_or_b32_e32 v168, 17, v132
	v_or_b32_e32 v169, 18, v132
	v_or_b32_e32 v170, 19, v132
	v_or_b32_e32 v171, 32, v132
	v_or_b32_e32 v172, 33, v132
	v_or_b32_e32 v173, 34, v132
	v_or_b32_e32 v174, 35, v132
	v_or_b32_e32 v175, 48, v132
	v_or_b32_e32 v176, 48, v131
	v_or_b32_e32 v178, 16, v131
	v_or_b32_e32 v179, 49, v132
	v_or_b32_e32 v180, 50, v132
	v_or_b32_e32 v181, 51, v132
	v_mul_u32_u24_e32 v183, 0x110, v182
	v_mul_u32_u24_e32 v185, 0x110, v134
	v_or_b32_e32 v186, 4, v134
	v_or_b32_e32 v187, 8, v134
	v_or_b32_e32 v188, 12, v134
	v_or_b32_e32 v189, 16, v134
	v_or_b32_e32 v190, 20, v134
	v_or_b32_e32 v191, 24, v134
	v_or_b32_e32 v195, 28, v134
	v_lshlrev_b32_e32 v136, 1, v32
	v_lshlrev_b32_e32 v138, 1, v0
	v_lshlrev_b32_e32 v196, 1, v1
	v_readlane_b32 s19, v253, 0
	s_branch .LBB0_231

; __device__ __forceinline__ float bflo(unsigned w) { return __uint_as_float(w << 16); }
; __device__ __forceinline__ float bfhi(unsigned w) { return __uint_as_float(w & 0xffff0000u); }
; __device__ __forceinline__ float siluf_(float x) { return x * __builtin_amdgcn_rcpf(1.0f + __builtin_amdgcn_exp2f(x * -1.44269504089f)); }
; __device__ __forceinline__ void d1_unit(const Params& p, int g, int l, int unit0, int nd1, unsigned char* lds0, const int tidx) {
;     ...
; #pragma unroll
;       for (int X = 0; X < 3; ++X) {
;           float y[16];
; #pragma unroll
;           for (int i = 0; i < 16; ++i) {
;               const f32x4 w = sCW[X * 128 + d0 + i];
;               float acc = 0.f;
; #pragma unroll
;               for (int j = 0; j < 4; ++j) { const unsigned wd = raw[X][j][i >> 3][(i >> 1) & 3]; acc += ((i & 1) ? bfhi(wd) : bflo(wd)) * w[j]; }
;               y[i] = c < nvalid ? siluf_(acc) : 0.f;
;           }
.LBB0_233:
	s_or_b64 exec, exec, s[2:3]
	ds_read_b128 v[198:201], v135 offset:240
	ds_read_b128 v[202:205], v135 offset:224
	ds_read_b128 v[206:209], v135 offset:208
	ds_read_b128 v[210:213], v135 offset:192
	ds_read_b128 v[214:217], v135 offset:176
	ds_read_b128 v[218:221], v135 offset:160
	ds_read_b128 v[222:225], v135 offset:144
	ds_read_b128 v[226:229], v135 offset:128
	ds_read_b128 v[120:123], v135 offset:112
	ds_read_b128 v[124:127], v135 offset:96
	ds_read_b128 v[112:115], v135 offset:80
	ds_read_b128 v[116:119], v135 offset:64
	ds_read_b128 v[100:103], v135
	ds_read_b128 v[96:99], v135 offset:16
	ds_read_b128 v[108:111], v135 offset:32
	ds_read_b128 v[104:107], v135 offset:48
	s_waitcnt vmcnt(1)
	v_lshlrev_b32_e32 v230, 16, v11
	v_and_b32_e32 v231, 0xffff0000, v11
	s_waitcnt lgkmcnt(14)
	v_mov_b32_e32 v232, v202
	v_mov_b32_e32 v233, v198
	v_pk_fma_f32 v[230:231], v[232:233], v[230:231], 0 op_sel_hi:[1,1,0]
	v_lshlrev_b32_e32 v232, 16, v7
	v_and_b32_e32 v233, 0xffff0000, v7
	v_mov_b32_e32 v198, v203
	v_pk_fma_f32 v[198:199], v[198:199], v[232:233], v[230:231]
	v_lshlrev_b32_e32 v202, 16, v47
	v_and_b32_e32 v203, 0xffff0000, v47
	v_mov_b32_e32 v230, v204
	v_mov_b32_e32 v231, v200
	v_pk_fma_f32 v[198:199], v[230:231], v[202:203], v[198:199]
	v_lshlrev_b32_e32 v202, 16, v39
	v_and_b32_e32 v203, 0xffff0000, v39
	v_mov_b32_e32 v200, v205
	v_pk_fma_f32 v[198:199], v[200:201], v[202:203], v[198:199]
	v_lshlrev_b32_e32 v202, 16, v10
	v_mul_f32_e32 v7, 0xbfb8aa3b, v199
	v_exp_f32_e32 v7, v7
	v_mul_f32_e32 v11, 0xbfb8aa3b, v198
	v_exp_f32_e32 v11, v11
	v_and_b32_e32 v203, 0xffff0000, v10
	v_add_f32_e32 v7, 1.0, v7
	v_rcp_f32_e32 v201, v7
	v_add_f32_e32 v7, 1.0, v11
	s_waitcnt lgkmcnt(12)
	v_mov_b32_e32 v10, v210
	v_mov_b32_e32 v11, v206
	v_pk_fma_f32 v[10:11], v[10:11], v[202:203], 0 op_sel_hi:[1,1,0]
	v_lshlrev_b32_e32 v202, 16, v6
	v_and_b32_e32 v203, 0xffff0000, v6
	v_mov_b32_e32 v206, v211
	v_rcp_f32_e32 v200, v7
	v_pk_fma_f32 v[6:7], v[206:207], v[202:203], v[10:11]
	v_lshlrev_b32_e32 v10, 16, v46
	v_and_b32_e32 v11, 0xffff0000, v46
	v_mov_b32_e32 v46, v212
	v_mov_b32_e32 v47, v208
	v_pk_fma_f32 v[6:7], v[46:47], v[10:11], v[6:7]
	v_lshlrev_b32_e32 v10, 16, v38
	v_and_b32_e32 v11, 0xffff0000, v38
	v_mov_b32_e32 v208, v213
	v_pk_fma_f32 v[10:11], v[208:209], v[10:11], v[6:7]
	v_lshlrev_b32_e32 v202, 16, v8
	v_mul_f32_e32 v6, 0xbfb8aa3b, v11
	v_exp_f32_e32 v38, v6
	v_mul_f32_e32 v6, 0xbfb8aa3b, v10
	v_exp_f32_e32 v39, v6
	v_pk_mul_f32 v[6:7], v[198:199], v[200:201]
	v_add_f32_e32 v38, 1.0, v38
	v_rcp_f32_e32 v47, v38
	v_add_f32_e32 v38, 1.0, v39
	v_rcp_f32_e32 v46, v38
	s_waitcnt lgkmcnt(10)
	v_mov_b32_e32 v198, v218
	v_mov_b32_e32 v199, v214
	v_mov_b32_e32 v214, v219
	v_pk_mul_f32 v[10:11], v[10:11], v[46:47]
	v_lshlrev_b32_e32 v46, 16, v9
	v_and_b32_e32 v47, 0xffff0000, v9
	v_pk_fma_f32 v[46:47], v[198:199], v[46:47], 0 op_sel_hi:[1,1,0]
	v_lshlrev_b32_e32 v198, 16, v5
	v_and_b32_e32 v199, 0xffff0000, v5
	v_pk_fma_f32 v[46:47], v[214:215], v[198:199], v[46:47]
	v_lshlrev_b32_e32 v198, 16, v45
	v_and_b32_e32 v199, 0xffff0000, v45
	v_mov_b32_e32 v200, v220
	v_mov_b32_e32 v201, v216
	v_pk_fma_f32 v[46:47], v[200:201], v[198:199], v[46:47]
	v_lshlrev_b32_e32 v198, 16, v37
	v_and_b32_e32 v199, 0xffff0000, v37
	v_mov_b32_e32 v216, v221
	v_pk_fma_f32 v[198:199], v[216:217], v[198:199], v[46:47]
	v_and_b32_e32 v203, 0xffff0000, v8
	v_mul_f32_e32 v5, 0xbfb8aa3b, v199
	v_exp_f32_e32 v5, v5
	v_mul_f32_e32 v9, 0xbfb8aa3b, v198
	v_exp_f32_e32 v9, v9
	s_waitcnt lgkmcnt(8)
	v_mov_b32_e32 v8, v226
	v_add_f32_e32 v5, 1.0, v5
	v_rcp_f32_e32 v201, v5
	v_add_f32_e32 v5, 1.0, v9
	v_mov_b32_e32 v9, v222
	v_pk_fma_f32 v[8:9], v[8:9], v[202:203], 0 op_sel_hi:[1,1,0]
	v_lshlrev_b32_e32 v202, 16, v4
	v_and_b32_e32 v203, 0xffff0000, v4
	v_mov_b32_e32 v222, v227
	v_rcp_f32_e32 v200, v5
	v_pk_fma_f32 v[4:5], v[222:223], v[202:203], v[8:9]
	v_lshlrev_b32_e32 v8, 16, v44
	v_and_b32_e32 v9, 0xffff0000, v44
	v_mov_b32_e32 v44, v228
	v_mov_b32_e32 v45, v224
	v_pk_fma_f32 v[4:5], v[44:45], v[8:9], v[4:5]
	v_lshlrev_b32_e32 v8, 16, v36
	v_and_b32_e32 v9, 0xffff0000, v36
	v_mov_b32_e32 v224, v229
	v_pk_fma_f32 v[8:9], v[224:225], v[8:9], v[4:5]
	v_cndmask_b32_e64 v11, 0, v11, s[50:51]
	v_mul_f32_e32 v4, 0xbfb8aa3b, v9
	v_exp_f32_e32 v36, v4
	v_mul_f32_e32 v4, 0xbfb8aa3b, v8
	v_exp_f32_e32 v44, v4
	v_pk_mul_f32 v[4:5], v[198:199], v[200:201]
	v_add_f32_e32 v36, 1.0, v36
	v_rcp_f32_e32 v37, v36
	v_add_f32_e32 v36, 1.0, v44
	v_rcp_f32_e32 v36, v36
	s_waitcnt lgkmcnt(6)
	v_mov_b32_e32 v198, v124
	v_mov_b32_e32 v199, v120
	v_mov_b32_e32 v120, v125
	v_pk_mul_f32 v[8:9], v[8:9], v[36:37]
	s_waitcnt vmcnt(0)
	v_lshlrev_b32_e32 v36, 16, v3
	v_and_b32_e32 v37, 0xffff0000, v3
	v_pk_fma_f32 v[36:37], v[198:199], v[36:37], 0 op_sel_hi:[1,1,0]
	v_lshlrev_b32_e32 v198, 16, v15
	v_and_b32_e32 v199, 0xffff0000, v15
	v_pk_fma_f32 v[36:37], v[120:121], v[198:199], v[36:37]
	v_lshlrev_b32_e32 v120, 16, v27
	v_and_b32_e32 v121, 0xffff0000, v27
	v_mov_b32_e32 v124, v126
	v_mov_b32_e32 v125, v122
	v_pk_fma_f32 v[36:37], v[124:125], v[120:121], v[36:37]
	v_lshlrev_b32_e32 v120, 16, v43
	v_and_b32_e32 v121, 0xffff0000, v43
	v_mov_b32_e32 v122, v127
	v_pk_fma_f32 v[36:37], v[122:123], v[120:121], v[36:37]
	v_lshlrev_b32_e32 v124, 16, v2
	v_mul_f32_e32 v3, 0xbfb8aa3b, v37
	v_exp_f32_e32 v3, v3
	v_mul_f32_e32 v15, 0xbfb8aa3b, v36
	v_exp_f32_e32 v15, v15
	v_and_b32_e32 v125, 0xffff0000, v2
	v_add_f32_e32 v3, 1.0, v3
	v_rcp_f32_e32 v123, v3
	v_add_f32_e32 v3, 1.0, v15
	v_rcp_f32_e32 v122, v3
	s_waitcnt lgkmcnt(4)
; __device__ __forceinline__ float bflo(unsigned w) { return __uint_as_float(w << 16); }
; __device__ __forceinline__ float bfhi(unsigned w) { return __uint_as_float(w & 0xffff0000u); }
; __device__ __forceinline__ float siluf_(float x) { return x * __builtin_amdgcn_rcpf(1.0f + __builtin_amdgcn_exp2f(x * -1.44269504089f)); }
; __device__ __forceinline__ void d1_unit(const Params& p, int g, int l, int unit0, int nd1, unsigned char* lds0, const int tidx) {
;     ...
;           for (int i = 0; i < 16; ++i) {
;               const f32x4 w = sCW[X * 128 + d0 + i];
;               float acc = 0.f;
; #pragma unroll
;               for (int j = 0; j < 4; ++j) { const unsigned wd = raw[X][j][i >> 3][(i >> 1) & 3]; acc += ((i & 1) ? bfhi(wd) : bflo(wd)) * w[j]; }
;               y[i] = c < nvalid ? siluf_(acc) : 0.f;
;           }
;           if (X < 2) {
;               float ss = 0.f;
; #pragma unroll
;               for (int i = 0; i < 16; ++i) ss += y[i] * y[i];
;               ss += __shfl_xor(ss, 1); ss += __shfl_xor(ss, 2); ss += __shfl_xor(ss, 4);
	v_mov_b32_e32 v2, v116
	v_mov_b32_e32 v3, v112
	v_pk_fma_f32 v[2:3], v[2:3], v[124:125], 0 op_sel_hi:[1,1,0]
	v_lshlrev_b32_e32 v124, 16, v14
	v_and_b32_e32 v125, 0xffff0000, v14
	v_mov_b32_e32 v112, v117
	v_pk_fma_f32 v[2:3], v[112:113], v[124:125], v[2:3]
	v_lshlrev_b32_e32 v14, 16, v26
	v_and_b32_e32 v15, 0xffff0000, v26
	v_mov_b32_e32 v26, v118
	v_mov_b32_e32 v27, v114
	v_pk_fma_f32 v[2:3], v[26:27], v[14:15], v[2:3]
	v_lshlrev_b32_e32 v14, 16, v42
	v_and_b32_e32 v15, 0xffff0000, v42
	v_mov_b32_e32 v114, v119
	v_pk_fma_f32 v[2:3], v[114:115], v[14:15], v[2:3]
	s_waitcnt lgkmcnt(0)
	v_mov_b32_e32 v43, v104
	v_mul_f32_e32 v14, 0xbfb8aa3b, v3
	v_exp_f32_e32 v26, v14
	v_mul_f32_e32 v14, 0xbfb8aa3b, v2
	v_exp_f32_e32 v42, v14
	v_mov_b32_e32 v104, v109
	v_add_f32_e32 v26, 1.0, v26
	v_rcp_f32_e32 v27, v26
	v_add_f32_e32 v26, 1.0, v42
	v_rcp_f32_e32 v26, v26
	v_mov_b32_e32 v42, v108
	v_pk_mul_f32 v[14:15], v[36:37], v[122:123]
	v_cndmask_b32_e64 v9, 0, v9, s[50:51]
	v_pk_mul_f32 v[2:3], v[2:3], v[26:27]
	v_lshlrev_b32_e32 v26, 16, v1
	v_and_b32_e32 v27, 0xffff0000, v1
	v_pk_fma_f32 v[26:27], v[42:43], v[26:27], 0 op_sel_hi:[1,1,0]
	v_lshlrev_b32_e32 v42, 16, v13
	v_and_b32_e32 v43, 0xffff0000, v13
	v_pk_fma_f32 v[26:27], v[104:105], v[42:43], v[26:27]
	v_lshlrev_b32_e32 v42, 16, v25
	v_and_b32_e32 v43, 0xffff0000, v25
	v_mov_b32_e32 v104, v110
	v_mov_b32_e32 v105, v106
	v_pk_fma_f32 v[26:27], v[104:105], v[42:43], v[26:27]
	v_lshlrev_b32_e32 v42, 16, v41
	v_and_b32_e32 v43, 0xffff0000, v41
	v_mov_b32_e32 v106, v111
	v_pk_fma_f32 v[26:27], v[106:107], v[42:43], v[26:27]
	v_lshlrev_b32_e32 v106, 16, v0
	v_mul_f32_e32 v1, 0xbfb8aa3b, v27
	v_exp_f32_e32 v1, v1
	v_mul_f32_e32 v13, 0xbfb8aa3b, v26
	v_exp_f32_e32 v13, v13
	v_and_b32_e32 v107, 0xffff0000, v0
	v_add_f32_e32 v1, 1.0, v1
	v_rcp_f32_e32 v105, v1
	v_add_f32_e32 v1, 1.0, v13
	v_rcp_f32_e32 v104, v1
	v_mov_b32_e32 v0, v100
	v_mov_b32_e32 v1, v96
	v_pk_fma_f32 v[0:1], v[0:1], v[106:107], 0 op_sel_hi:[1,1,0]
	v_lshlrev_b32_e32 v106, 16, v12
	v_and_b32_e32 v107, 0xffff0000, v12
	v_mov_b32_e32 v96, v101
	v_pk_fma_f32 v[0:1], v[96:97], v[106:107], v[0:1]
	v_lshlrev_b32_e32 v12, 16, v24
	v_and_b32_e32 v13, 0xffff0000, v24
	v_mov_b32_e32 v24, v102
	v_mov_b32_e32 v25, v98
	v_pk_fma_f32 v[0:1], v[24:25], v[12:13], v[0:1]
	v_lshlrev_b32_e32 v12, 16, v40
	v_and_b32_e32 v13, 0xffff0000, v40
	v_mov_b32_e32 v98, v103
	v_pk_fma_f32 v[0:1], v[98:99], v[12:13], v[0:1]
	v_cndmask_b32_e64 v3, 0, v3, s[50:51]
	v_mul_f32_e32 v12, 0xbfb8aa3b, v1
	v_exp_f32_e32 v24, v12
	v_mul_f32_e32 v12, 0xbfb8aa3b, v0
	v_exp_f32_e32 v40, v12
	v_pk_mul_f32 v[12:13], v[26:27], v[104:105]
	v_add_f32_e32 v24, 1.0, v24
	v_rcp_f32_e32 v25, v24
	v_add_f32_e32 v24, 1.0, v40
	v_rcp_f32_e32 v24, v24
	v_cndmask_b32_e64 v13, 0, v13, s[50:51]
	v_cndmask_b32_e64 v12, 0, v12, s[50:51]
	v_pk_mul_f32 v[26:27], v[12:13], v[12:13]
	v_pk_mul_f32 v[0:1], v[0:1], v[24:25]
	v_cndmask_b32_e64 v2, 0, v2, s[50:51]
	v_cndmask_b32_e64 v1, 0, v1, s[50:51]
	v_cndmask_b32_e64 v0, 0, v0, s[50:51]
	v_pk_mul_f32 v[24:25], v[0:1], v[0:1]
	v_pk_mul_f32 v[42:43], v[2:3], v[2:3]
	v_add_f32_e32 v24, v25, v24
	v_add_f32_e32 v24, v26, v24
	v_add_f32_e32 v24, v27, v24
	v_cndmask_b32_e64 v15, 0, v15, s[50:51]
	v_cndmask_b32_e64 v14, 0, v14, s[50:51]
	v_add_f32_e32 v24, v42, v24
	v_pk_mul_f32 v[36:37], v[14:15], v[14:15]
	v_add_f32_e32 v24, v43, v24
	v_cndmask_b32_e64 v8, 0, v8, s[50:51]
	v_add_f32_e32 v24, v36, v24
	v_pk_mul_f32 v[120:121], v[8:9], v[8:9]
	v_add_f32_e32 v24, v37, v24
	v_cndmask_b32_e64 v5, 0, v5, s[50:51]
	v_cndmask_b32_e64 v4, 0, v4, s[50:51]
	v_add_f32_e32 v24, v120, v24
	v_pk_mul_f32 v[44:45], v[4:5], v[4:5]
	v_add_f32_e32 v24, v121, v24
	v_cndmask_b32_e64 v10, 0, v10, s[50:51]
	v_add_f32_e32 v24, v44, v24
	v_and_b32_e32 v197, 64, v244
	v_pk_mul_f32 v[46:47], v[10:11], v[10:11]
	v_add_f32_e32 v24, v45, v24
	v_xor_b32_e32 v139, 1, v244
	v_add_u32_e32 v197, 64, v197
	v_cndmask_b32_e64 v7, 0, v7, s[50:51]
	v_cndmask_b32_e64 v6, 0, v6, s[50:51]
	v_add_f32_e32 v24, v46, v24
	v_cmp_lt_i32_e64 s[2:3], v139, v197
	v_pk_mul_f32 v[38:39], v[6:7], v[6:7]
	v_add_f32_e32 v24, v47, v24
	v_cndmask_b32_e64 v139, v244, v139, s[2:3]
	v_add_f32_e32 v24, v38, v24
	v_lshlrev_b32_e32 v139, 2, v139
	v_add_f32_e32 v24, v39, v24
	ds_bpermute_b32 v25, v139, v24
	v_xor_b32_e32 v26, 2, v244
	v_cmp_lt_i32_e64 s[2:3], v26, v197
	s_mov_b32 s14, 0x800000
	v_mad_u32_u24 v44, v192, s75, v137
	v_cndmask_b32_e64 v26, v244, v26, s[2:3]
	v_lshlrev_b32_e32 v45, 2, v26
	s_waitcnt lgkmcnt(0)
	v_add_f32_e32 v24, v24, v25
	ds_bpermute_b32 v25, v45, v24
	v_xor_b32_e32 v26, 4, v244
	v_cmp_lt_i32_e64 s[2:3], v26, v197
	v_and_b32_e32 v41, 0xffff0000, v32
	v_and_b32_e32 v40, 0xffff0000, v16
	v_cndmask_b32_e64 v26, v244, v26, s[2:3]
	v_lshlrev_b32_e32 v120, 2, v26
	s_waitcnt lgkmcnt(0)
	v_add_f32_e32 v24, v24, v25
	ds_bpermute_b32 v25, v120, v24
	s_mov_b64 vcc, s[50:51]
	s_waitcnt lgkmcnt(0)
; __device__ __forceinline__ unsigned cvt_pk_bf16(float lo, float hi) { const f32x2 v = {lo, hi}; const bf16v2_t b = __builtin_convertvector(v, bf16v2_t); return __builtin_bit_cast(unsigned, b); }
; __device__ __forceinline__ float bflo(unsigned w) { return __uint_as_float(w << 16); }
; __device__ __forceinline__ float bfhi(unsigned w) { return __uint_as_float(w & 0xffff0000u); }
; __device__ __forceinline__ float siluf_(float x) { return x * __builtin_amdgcn_rcpf(1.0f + __builtin_amdgcn_exp2f(x * -1.44269504089f)); }
; __device__ __forceinline__ void d1_unit(const Params& p, int g, int l, int unit0, int nd1, unsigned char* lds0, const int tidx) {
;     ...
;           for (int i = 0; i < 16; ++i) {
;               const f32x4 w = sCW[X * 128 + d0 + i];
;               float acc = 0.f;
; #pragma unroll
;               for (int j = 0; j < 4; ++j) { const unsigned wd = raw[X][j][i >> 3][(i >> 1) & 3]; acc += ((i & 1) ? bfhi(wd) : bflo(wd)) * w[j]; }
;               y[i] = c < nvalid ? siluf_(acc) : 0.f;
;           }
;           if (X < 2) {
;               float ss = 0.f;
; #pragma unroll
;               for (int i = 0; i < 16; ++i) ss += y[i] * y[i];
;               ss += __shfl_xor(ss, 1); ss += __shfl_xor(ss, 2); ss += __shfl_xor(ss, 4);
;               const float sc = rsqrtf(ss + EPS) * (X == 0 ? 0.08838834764831845f : 1.0f);
; #pragma unroll
;               for (int i = 0; i < 16; ++i) y[i] *= sc;
;           }
;           bf16_t* dst = (X == 0 ? sq : (X == 1 ? sk : sv)) + c * 136 + d0;
;           u32x4 w0, w1;
;           w0.x = cvt_pk_bf16(y[0], y[1]); w0.y = cvt_pk_bf16(y[2], y[3]); w0.z = cvt_pk_bf16(y[4], y[5]); w0.w = cvt_pk_bf16(y[6], y[7]);
;           w1.x = cvt_pk_bf16(y[8], y[9]); w1.y = cvt_pk_bf16(y[10], y[11]); w1.z = cvt_pk_bf16(y[12], y[13]); w1.w = cvt_pk_bf16(y[14], y[15]);
;           *(u32x4*)dst = w0; *(u32x4*)(dst + 8) = w1;
	v_add_f32_e32 v24, v24, v25
	v_add_f32_e32 v24, 0x358637bd, v24
	v_mul_f32_e32 v25, 0x4b800000, v24
	v_cmp_gt_f32_e64 s[2:3], s14, v24
	s_nop 1
	v_cndmask_b32_e64 v24, v24, v25, s[2:3]
	v_rsq_f32_e32 v24, v24
	s_nop 0
	v_mul_f32_e32 v25, 0x45800000, v24
	v_cndmask_b32_e64 v24, v24, v25, s[2:3]
	v_mul_f32_e32 v24, 0x3db504f3, v24
	v_pk_mul_f32 v[26:27], v[6:7], v[24:25] op_sel_hi:[1,0]
	v_pk_mul_f32 v[6:7], v[10:11], v[24:25] op_sel_hi:[1,0]
	v_pk_mul_f32 v[10:11], v[4:5], v[24:25] op_sel_hi:[1,0]
	v_pk_mul_f32 v[4:5], v[8:9], v[24:25] op_sel_hi:[1,0]
	v_pk_mul_f32 v[8:9], v[14:15], v[24:25] op_sel_hi:[1,0]
	v_pk_mul_f32 v[2:3], v[2:3], v[24:25] op_sel_hi:[1,0]
	v_pk_mul_f32 v[12:13], v[12:13], v[24:25] op_sel_hi:[1,0]
	v_pk_mul_f32 v[0:1], v[0:1], v[24:25] op_sel_hi:[1,0]
	v_cvt_pk_bf16_f32 v2, v2, v3
	v_cvt_pk_bf16_f32 v0, v0, v1
	v_cvt_pk_bf16_f32 v1, v12, v13
	v_cvt_pk_bf16_f32 v3, v8, v9
	v_cvt_pk_bf16_f32 v4, v4, v5
	v_cvt_pk_bf16_f32 v5, v10, v11
	v_cvt_pk_bf16_f32 v6, v6, v7
	v_cvt_pk_bf16_f32 v7, v26, v27
	ds_write_b128 v44, v[0:3]
	ds_write_b128 v44, v[4:7] offset:16
	ds_read_b128 v[4:7], v135 offset:2416
	ds_read_b128 v[8:11], v135 offset:2400
	ds_read_b128 v[96:99], v135 offset:2384
	ds_read_b128 v[100:103], v135 offset:2368
	ds_read_b128 v[104:107], v135 offset:2352
	ds_read_b128 v[108:111], v135 offset:2336
	ds_read_b128 v[112:115], v135 offset:2320
	ds_read_b128 v[116:119], v135 offset:2304
	ds_read_b128 v[0:3], v135 offset:2176
	ds_read_b128 v[12:15], v135 offset:2192
	ds_read_b128 v[24:27], v135 offset:2288
	ds_read_b128 v[36:39], v135 offset:2272
	s_waitcnt lgkmcnt(10)
	v_mov_b32_e32 v42, v8
	v_mov_b32_e32 v43, v4
	s_waitcnt lgkmcnt(2)
	v_pk_mul_f32 v[12:13], v[12:13], v[40:41]
	v_and_b32_e32 v41, 0xffff0000, v31
	v_add_f32_e32 v12, 0, v12
	v_add_f32_e32 v40, v13, v12
	v_and_b32_e32 v13, 0xffff0000, v72
	v_and_b32_e32 v12, 0xffff0000, v56
	v_pk_mul_f32 v[12:13], v[14:15], v[12:13]
	v_mov_b32_e32 v4, v9
	v_add_f32_e32 v12, v12, v40
	v_add_f32_e32 v46, v13, v12
	v_mul_f32_e32 v12, 0xbfb8aa3b, v46
	v_exp_f32_e32 v40, v12
	v_lshlrev_b32_e32 v13, 16, v32
	v_lshlrev_b32_e32 v12, 16, v16
	v_pk_mul_f32 v[0:1], v[0:1], v[12:13]
	v_add_f32_e32 v40, 1.0, v40
	v_rcp_f32_e32 v47, v40
	v_lshlrev_b32_e32 v40, 16, v31
	v_pk_fma_f32 v[40:41], v[42:43], v[40:41], 0 op_sel_hi:[1,1,0]
	v_lshlrev_b32_e32 v42, 16, v23
	v_and_b32_e32 v43, 0xffff0000, v23
	v_pk_fma_f32 v[4:5], v[4:5], v[42:43], v[40:41]
	v_lshlrev_b32_e32 v8, 16, v71
	v_and_b32_e32 v9, 0xffff0000, v71
	v_mov_b32_e32 v40, v10
	v_mov_b32_e32 v41, v6
	v_add_f32_e32 v0, 0, v0
	v_pk_fma_f32 v[4:5], v[40:41], v[8:9], v[4:5]
	v_lshlrev_b32_e32 v8, 16, v67
	v_and_b32_e32 v9, 0xffff0000, v67
	v_mov_b32_e32 v6, v11
	v_add_f32_e32 v12, v1, v0
	v_lshlrev_b32_e32 v1, 16, v72
	v_lshlrev_b32_e32 v0, 16, v56
	v_pk_fma_f32 v[40:41], v[6:7], v[8:9], v[4:5]
	v_pk_mul_f32 v[0:1], v[2:3], v[0:1]
	v_mul_f32_e32 v4, 0xbfb8aa3b, v41
	v_add_f32_e32 v0, v0, v12
	v_exp_f32_e32 v4, v4
	v_mul_f32_e32 v5, 0xbfb8aa3b, v40
	v_add_f32_e32 v16, v1, v0
	v_exp_f32_e32 v5, v5
	v_mul_f32_e32 v0, 0xbfb8aa3b, v16
	v_exp_f32_e32 v32, v0
	v_add_f32_e32 v4, 1.0, v4
	v_rcp_f32_e32 v43, v4
	v_add_f32_e32 v4, 1.0, v5
	v_rcp_f32_e32 v42, v4
	v_add_f32_e32 v32, 1.0, v32
	v_rcp_f32_e32 v23, v32
	v_mov_b32_e32 v31, v96
	v_pk_mul_f32 v[40:41], v[40:41], v[42:43]
	v_lshlrev_b32_e32 v42, 16, v30
	v_and_b32_e32 v43, 0xffff0000, v30
	v_mov_b32_e32 v30, v100
	v_pk_fma_f32 v[30:31], v[30:31], v[42:43], 0 op_sel_hi:[1,1,0]
	v_lshlrev_b32_e32 v42, 16, v22
	v_and_b32_e32 v43, 0xffff0000, v22
	v_mov_b32_e32 v96, v101
	v_mul_f32_e32 v56, v16, v23
	v_pk_fma_f32 v[22:23], v[96:97], v[42:43], v[30:31]
	v_lshlrev_b32_e32 v30, 16, v70
	v_and_b32_e32 v31, 0xffff0000, v70
	v_mov_b32_e32 v42, v102
	v_mov_b32_e32 v43, v98
	v_pk_fma_f32 v[22:23], v[42:43], v[30:31], v[22:23]
	v_lshlrev_b32_e32 v30, 16, v66
	v_and_b32_e32 v31, 0xffff0000, v66
	v_mov_b32_e32 v98, v103
	v_pk_fma_f32 v[30:31], v[98:99], v[30:31], v[22:23]
	v_mul_f32_e32 v32, v46, v47
	v_mul_f32_e32 v16, 0xbfb8aa3b, v31
	v_exp_f32_e32 v16, v16
	v_mul_f32_e32 v22, 0xbfb8aa3b, v30
	v_exp_f32_e32 v42, v22
	v_lshlrev_b32_e32 v46, 16, v29
	v_and_b32_e32 v47, 0xffff0000, v29
	v_mov_b32_e32 v66, v108
	v_mov_b32_e32 v67, v104
	v_pk_fma_f32 v[46:47], v[66:67], v[46:47], 0 op_sel_hi:[1,1,0]
	v_lshlrev_b32_e32 v66, 16, v21
	v_and_b32_e32 v67, 0xffff0000, v21
	v_mov_b32_e32 v104, v109
	v_pk_fma_f32 v[46:47], v[104:105], v[66:67], v[46:47]
	v_lshlrev_b32_e32 v66, 16, v69
	v_and_b32_e32 v67, 0xffff0000, v69
	v_mov_b32_e32 v70, v110
	v_mov_b32_e32 v71, v106
	v_add_f32_e32 v16, 1.0, v16
	v_pk_fma_f32 v[46:47], v[70:71], v[66:67], v[46:47]
	v_lshlrev_b32_e32 v66, 16, v65
	v_and_b32_e32 v67, 0xffff0000, v65
	v_mov_b32_e32 v106, v111
	v_rcp_f32_e32 v43, v16
	v_add_f32_e32 v16, 1.0, v42
	v_pk_fma_f32 v[46:47], v[106:107], v[66:67], v[46:47]
	v_rcp_f32_e32 v42, v16
	v_mul_f32_e32 v16, 0xbfb8aa3b, v47
	v_exp_f32_e32 v16, v16
	v_mul_f32_e32 v21, 0xbfb8aa3b, v46
	v_exp_f32_e32 v21, v21
	v_pk_mul_f32 v[30:31], v[30:31], v[42:43]
	v_add_f32_e32 v16, 1.0, v16
	v_rcp_f32_e32 v43, v16
	v_add_f32_e32 v16, 1.0, v21
	v_rcp_f32_e32 v42, v16
	v_mov_b32_e32 v29, v112
	v_mov_b32_e32 v112, v117
	v_and_b32_e32 v65, 0xffff0000, v19
	v_pk_mul_f32 v[42:43], v[46:47], v[42:43]
	v_lshlrev_b32_e32 v46, 16, v28
	v_and_b32_e32 v47, 0xffff0000, v28
	v_mov_b32_e32 v28, v116
	v_pk_fma_f32 v[28:29], v[28:29], v[46:47], 0 op_sel_hi:[1,1,0]
	v_lshlrev_b32_e32 v46, 16, v20
	v_and_b32_e32 v47, 0xffff0000, v20
	v_pk_fma_f32 v[20:21], v[112:113], v[46:47], v[28:29]
	v_lshlrev_b32_e32 v28, 16, v68
	v_and_b32_e32 v29, 0xffff0000, v68
	v_mov_b32_e32 v46, v118
	v_mov_b32_e32 v47, v114
	v_pk_fma_f32 v[20:21], v[46:47], v[28:29], v[20:21]
	v_lshlrev_b32_e32 v28, 16, v64
	v_and_b32_e32 v29, 0xffff0000, v64
	v_mov_b32_e32 v114, v119
	v_pk_fma_f32 v[20:21], v[114:115], v[28:29], v[20:21]
	v_lshlrev_b32_e32 v64, 16, v19
	v_mul_f32_e32 v16, 0xbfb8aa3b, v21
	v_exp_f32_e32 v16, v16
	v_mul_f32_e32 v28, 0xbfb8aa3b, v20
	v_exp_f32_e32 v46, v28
	s_waitcnt lgkmcnt(0)
; __device__ __forceinline__ unsigned cvt_pk_bf16(float lo, float hi) { const f32x2 v = {lo, hi}; const bf16v2_t b = __builtin_convertvector(v, bf16v2_t); return __builtin_bit_cast(unsigned, b); }
; __device__ __forceinline__ float bflo(unsigned w) { return __uint_as_float(w << 16); }
; __device__ __forceinline__ float bfhi(unsigned w) { return __uint_as_float(w & 0xffff0000u); }
; __device__ __forceinline__ float siluf_(float x) { return x * __builtin_amdgcn_rcpf(1.0f + __builtin_amdgcn_exp2f(x * -1.44269504089f)); }
; __device__ __forceinline__ void d1_unit(const Params& p, int g, int l, int unit0, int nd1, unsigned char* lds0, const int tidx) {
;     ...
;           for (int i = 0; i < 16; ++i) {
;               const f32x4 w = sCW[X * 128 + d0 + i];
;               float acc = 0.f;
; #pragma unroll
;               for (int j = 0; j < 4; ++j) { const unsigned wd = raw[X][j][i >> 3][(i >> 1) & 3]; acc += ((i & 1) ? bfhi(wd) : bflo(wd)) * w[j]; }
;               y[i] = c < nvalid ? siluf_(acc) : 0.f;
;           }
;           if (X < 2) {
;               float ss = 0.f;
; #pragma unroll
;               for (int i = 0; i < 16; ++i) ss += y[i] * y[i];
;               ss += __shfl_xor(ss, 1); ss += __shfl_xor(ss, 2); ss += __shfl_xor(ss, 4);
;               const float sc = rsqrtf(ss + EPS) * (X == 0 ? 0.08838834764831845f : 1.0f);
; #pragma unroll
;               for (int i = 0; i < 16; ++i) y[i] *= sc;
;           }
;           bf16_t* dst = (X == 0 ? sq : (X == 1 ? sk : sv)) + c * 136 + d0;
;           u32x4 w0, w1;
;           w0.x = cvt_pk_bf16(y[0], y[1]); w0.y = cvt_pk_bf16(y[2], y[3]); w0.z = cvt_pk_bf16(y[4], y[5]); w0.w = cvt_pk_bf16(y[6], y[7]);
;           w1.x = cvt_pk_bf16(y[8], y[9]); w1.y = cvt_pk_bf16(y[10], y[11]); w1.z = cvt_pk_bf16(y[12], y[13]); w1.w = cvt_pk_bf16(y[14], y[15]);
;           *(u32x4*)dst = w0; *(u32x4*)(dst + 8) = w1;
	v_mov_b32_e32 v68, v36
	v_mov_b32_e32 v69, v24
	v_pk_fma_f32 v[64:65], v[68:69], v[64:65], 0 op_sel_hi:[1,1,0]
	v_lshlrev_b32_e32 v68, 16, v35
	v_and_b32_e32 v69, 0xffff0000, v35
	v_mov_b32_e32 v24, v37
	v_pk_fma_f32 v[24:25], v[24:25], v[68:69], v[64:65]
	v_lshlrev_b32_e32 v36, 16, v59
	v_and_b32_e32 v37, 0xffff0000, v59
	v_mov_b32_e32 v64, v38
	v_mov_b32_e32 v65, v26
	v_add_f32_e32 v16, 1.0, v16
	v_pk_fma_f32 v[24:25], v[64:65], v[36:37], v[24:25]
	v_lshlrev_b32_e32 v36, 16, v75
	v_and_b32_e32 v37, 0xffff0000, v75
	v_mov_b32_e32 v26, v39
	v_rcp_f32_e32 v47, v16
	v_add_f32_e32 v16, 1.0, v46
	v_pk_fma_f32 v[24:25], v[26:27], v[36:37], v[24:25]
	v_rcp_f32_e32 v46, v16
	v_mul_f32_e32 v16, 0xbfb8aa3b, v25
	v_exp_f32_e32 v16, v16
	v_mul_f32_e32 v19, 0xbfb8aa3b, v24
	v_exp_f32_e32 v19, v19
	ds_read_b128 v[0:3], v135 offset:2256
	ds_read_b128 v[12:15], v135 offset:2240
	v_add_f32_e32 v16, 1.0, v16
	v_rcp_f32_e32 v27, v16
	v_add_f32_e32 v16, 1.0, v19
	v_rcp_f32_e32 v26, v16
	s_waitcnt lgkmcnt(1)
	v_mov_b32_e32 v19, v0
	s_waitcnt lgkmcnt(0)
	v_mov_b32_e32 v0, v13
	v_and_b32_e32 v13, 0xffff0000, v58
	v_pk_mul_f32 v[24:25], v[24:25], v[26:27]
	v_lshlrev_b32_e32 v26, 16, v18
	v_and_b32_e32 v27, 0xffff0000, v18
	v_mov_b32_e32 v18, v12
	v_pk_fma_f32 v[18:19], v[18:19], v[26:27], 0 op_sel_hi:[1,1,0]
	v_lshlrev_b32_e32 v26, 16, v34
	v_and_b32_e32 v27, 0xffff0000, v34
	v_pk_fma_f32 v[0:1], v[0:1], v[26:27], v[18:19]
	v_lshlrev_b32_e32 v12, 16, v58
	v_mov_b32_e32 v18, v14
	v_mov_b32_e32 v19, v2
	v_pk_fma_f32 v[0:1], v[18:19], v[12:13], v[0:1]
	v_lshlrev_b32_e32 v12, 16, v74
	v_and_b32_e32 v13, 0xffff0000, v74
	v_mov_b32_e32 v2, v15
	v_pk_fma_f32 v[0:1], v[2:3], v[12:13], v[0:1]
	ds_read_b128 v[8:11], v135 offset:2208
	ds_read_b128 v[4:7], v135 offset:2224
	v_mul_f32_e32 v2, 0xbfb8aa3b, v1
	v_exp_f32_e32 v12, v2
	v_mul_f32_e32 v2, 0xbfb8aa3b, v0
	v_exp_f32_e32 v14, v2
	v_and_b32_e32 v15, 0xffff0000, v17
	v_add_f32_e32 v12, 1.0, v12
	v_rcp_f32_e32 v13, v12
	v_add_f32_e32 v12, 1.0, v14
	v_lshlrev_b32_e32 v14, 16, v17
	s_waitcnt lgkmcnt(1)
	v_mov_b32_e32 v16, v8
	s_waitcnt lgkmcnt(0)
	v_mov_b32_e32 v17, v4
	v_pk_fma_f32 v[14:15], v[16:17], v[14:15], 0 op_sel_hi:[1,1,0]
	v_lshlrev_b32_e32 v16, 16, v33
	v_and_b32_e32 v17, 0xffff0000, v33
	v_mov_b32_e32 v4, v9
	v_pk_fma_f32 v[4:5], v[4:5], v[16:17], v[14:15]
	v_lshlrev_b32_e32 v8, 16, v57
	v_and_b32_e32 v9, 0xffff0000, v57
	v_mov_b32_e32 v14, v10
	v_mov_b32_e32 v15, v6
	v_pk_fma_f32 v[4:5], v[14:15], v[8:9], v[4:5]
	v_lshlrev_b32_e32 v8, 16, v73
	v_and_b32_e32 v9, 0xffff0000, v73
	v_mov_b32_e32 v6, v11
	v_pk_fma_f32 v[4:5], v[6:7], v[8:9], v[4:5]
	v_rcp_f32_e32 v12, v12
	v_mul_f32_e32 v6, 0xbfb8aa3b, v5
	v_exp_f32_e32 v6, v6
	v_mul_f32_e32 v7, 0xbfb8aa3b, v4
	v_exp_f32_e32 v8, v7
	v_pk_mul_f32 v[0:1], v[0:1], v[12:13]
	v_add_f32_e32 v6, 1.0, v6
	v_rcp_f32_e32 v7, v6
	v_add_f32_e32 v6, 1.0, v8
	v_rcp_f32_e32 v6, v6
	v_cndmask_b32_e64 v12, 0, v56, s[50:51]
	v_cndmask_b32_e64 v11, 0, v32, s[50:51]
	v_mul_f32_e32 v10, v12, v12
	v_pk_mul_f32 v[4:5], v[4:5], v[6:7]
	v_fmac_f32_e32 v10, v11, v11
	v_cndmask_b32_e64 v5, 0, v5, s[50:51]
	v_cndmask_b32_e64 v4, 0, v4, s[50:51]
	v_pk_mul_f32 v[6:7], v[4:5], v[4:5]
	v_cndmask_b32_e64 v1, 0, v1, s[50:51]
	v_cndmask_b32_e64 v0, 0, v0, s[50:51]
	v_add_f32_e32 v6, v6, v10
	v_pk_mul_f32 v[8:9], v[0:1], v[0:1]
	v_add_f32_e32 v6, v7, v6
	v_cndmask_b32_e64 v25, 0, v25, s[50:51]
	v_cndmask_b32_e64 v24, 0, v24, s[50:51]
	v_add_f32_e32 v6, v8, v6
	v_pk_mul_f32 v[20:21], v[20:21], v[46:47]
	v_pk_mul_f32 v[2:3], v[24:25], v[24:25]
	v_add_f32_e32 v6, v9, v6
	v_cndmask_b32_e64 v21, 0, v21, s[50:51]
	v_cndmask_b32_e64 v20, 0, v20, s[50:51]
	v_add_f32_e32 v2, v2, v6
	v_pk_mul_f32 v[36:37], v[20:21], v[20:21]
	v_add_f32_e32 v2, v3, v2
	v_cndmask_b32_e64 v43, 0, v43, s[50:51]
	v_cndmask_b32_e64 v42, 0, v42, s[50:51]
	v_add_f32_e32 v2, v36, v2
	v_pk_mul_f32 v[28:29], v[42:43], v[42:43]
	v_add_f32_e32 v2, v37, v2
	v_cndmask_b32_e64 v31, 0, v31, s[50:51]
	v_cndmask_b32_e64 v30, 0, v30, s[50:51]
	v_add_f32_e32 v2, v28, v2
	v_pk_mul_f32 v[66:67], v[30:31], v[30:31]
	v_add_f32_e32 v2, v29, v2
	v_cndmask_b32_e64 v41, 0, v41, s[50:51]
	v_cndmask_b32_e64 v40, 0, v40, s[50:51]
	v_add_f32_e32 v2, v66, v2
	v_pk_mul_f32 v[22:23], v[40:41], v[40:41]
	v_add_f32_e32 v2, v67, v2
	v_add_f32_e32 v2, v22, v2
	v_add_f32_e32 v2, v23, v2
	ds_bpermute_b32 v3, v139, v2
	v_lshlrev_b32_e32 v18, 16, v63
	v_and_b32_e32 v19, 0xffff0000, v63
	v_lshlrev_b32_e32 v22, 16, v52
	v_and_b32_e32 v23, 0xffff0000, v52
	s_waitcnt lgkmcnt(0)
	v_add_f32_e32 v2, v2, v3
	ds_bpermute_b32 v3, v45, v2
	v_lshlrev_b32_e32 v28, 16, v55
	v_and_b32_e32 v29, 0xffff0000, v55
	s_waitcnt lgkmcnt(0)
	v_add_f32_e32 v2, v2, v3
	ds_bpermute_b32 v3, v120, v2
	s_waitcnt lgkmcnt(0)
	v_add_f32_e32 v2, v2, v3
	v_add_f32_e32 v2, 0x358637bd, v2
	v_mul_f32_e32 v3, 0x4b800000, v2
	v_cmp_gt_f32_e64 s[2:3], s14, v2
	s_xor_b64 s[14:15], s[70:71], -1
	s_mov_b64 s[70:71], 0
	v_cndmask_b32_e64 v2, v2, v3, s[2:3]
	v_rsq_f32_e32 v2, v2
	s_nop 0
	v_mul_f32_e32 v3, 0x45800000, v2
	v_cndmask_b32_e64 v10, v2, v3, s[2:3]
	v_mov_b32_e32 v13, v10
	v_pk_mul_f32 v[2:3], v[10:11], v[12:13]
	v_pk_mul_f32 v[4:5], v[4:5], v[10:11] op_sel_hi:[1,0]
	v_pk_mul_f32 v[6:7], v[0:1], v[10:11] op_sel_hi:[1,0]
	v_pk_mul_f32 v[8:9], v[24:25], v[10:11] op_sel_hi:[1,0]
	v_pk_mul_f32 v[12:13], v[20:21], v[10:11] op_sel_hi:[1,0]
	v_pk_mul_f32 v[14:15], v[42:43], v[10:11] op_sel_hi:[1,0]
	v_pk_mul_f32 v[16:17], v[30:31], v[10:11] op_sel_hi:[1,0]
	v_pk_mul_f32 v[10:11], v[40:41], v[10:11] op_sel_hi:[1,0]
	v_cvt_pk_bf16_f32 v0, v2, v3
	v_cvt_pk_bf16_f32 v1, v4, v5
	v_cvt_pk_bf16_f32 v2, v6, v7
	v_cvt_pk_bf16_f32 v3, v8, v9
	v_cvt_pk_bf16_f32 v4, v12, v13
	v_cvt_pk_bf16_f32 v5, v14, v15
	v_cvt_pk_bf16_f32 v6, v16, v17
	v_cvt_pk_bf16_f32 v7, v10, v11
	ds_write_b128 v44, v[0:3] offset:17408
	ds_write_b128 v44, v[4:7] offset:17424
	ds_read_b128 v[0:3], v135 offset:4352
	ds_read_b128 v[4:7], v135 offset:4368
	v_lshlrev_b32_e32 v8, 16, v60
	v_and_b32_e32 v9, 0xffff0000, v60
	v_lshlrev_b32_e32 v12, 16, v61
	s_waitcnt lgkmcnt(1)
; __device__ __forceinline__ float bflo(unsigned w) { return __uint_as_float(w << 16); }
; __device__ __forceinline__ float bfhi(unsigned w) { return __uint_as_float(w & 0xffff0000u); }
; __device__ __forceinline__ float siluf_(float x) { return x * __builtin_amdgcn_rcpf(1.0f + __builtin_amdgcn_exp2f(x * -1.44269504089f)); }
; __device__ __forceinline__ void d1_unit(const Params& p, int g, int l, int unit0, int nd1, unsigned char* lds0, const int tidx) {
;     ...
;           for (int i = 0; i < 16; ++i) {
;               const f32x4 w = sCW[X * 128 + d0 + i];
;               float acc = 0.f;
; #pragma unroll
;               for (int j = 0; j < 4; ++j) { const unsigned wd = raw[X][j][i >> 3][(i >> 1) & 3]; acc += ((i & 1) ? bfhi(wd) : bflo(wd)) * w[j]; }
;               y[i] = c < nvalid ? siluf_(acc) : 0.f;
;           }
	v_mov_b32_e32 v10, v0
	s_waitcnt lgkmcnt(0)
	v_mov_b32_e32 v11, v4
	v_pk_fma_f32 v[8:9], v[10:11], v[8:9], 0 op_sel_hi:[1,1,0]
	v_lshlrev_b32_e32 v10, 16, v80
	v_and_b32_e32 v11, 0xffff0000, v80
	v_mov_b32_e32 v4, v1
	v_pk_fma_f32 v[0:1], v[4:5], v[10:11], v[8:9]
	v_lshlrev_b32_e32 v4, 16, v88
	v_and_b32_e32 v5, 0xffff0000, v88
	v_mov_b32_e32 v8, v2
	v_mov_b32_e32 v9, v6
	v_pk_fma_f32 v[0:1], v[8:9], v[4:5], v[0:1]
	v_lshlrev_b32_e32 v4, 16, v92
	v_and_b32_e32 v5, 0xffff0000, v92
	v_mov_b32_e32 v6, v3
	v_pk_fma_f32 v[8:9], v[6:7], v[4:5], v[0:1]
	v_and_b32_e32 v13, 0xffff0000, v61
	v_mul_f32_e32 v0, 0xbfb8aa3b, v8
	v_exp_f32_e32 v10, v0
	v_mul_f32_e32 v0, 0xbfb8aa3b, v9
	v_exp_f32_e32 v11, v0
	ds_read_b128 v[0:3], v135 offset:4384
	ds_read_b128 v[4:7], v135 offset:4400
	v_add_f32_e32 v10, 1.0, v10
	v_rcp_f32_e32 v10, v10
	v_add_f32_e32 v11, 1.0, v11
	s_waitcnt lgkmcnt(1)
	v_mov_b32_e32 v14, v0
	s_waitcnt lgkmcnt(0)
	v_mov_b32_e32 v15, v4
	v_pk_fma_f32 v[12:13], v[14:15], v[12:13], 0 op_sel_hi:[1,1,0]
	v_lshlrev_b32_e32 v14, 16, v81
	v_and_b32_e32 v15, 0xffff0000, v81
	v_mov_b32_e32 v4, v1
	v_pk_fma_f32 v[0:1], v[4:5], v[14:15], v[12:13]
	v_lshlrev_b32_e32 v4, 16, v89
	v_and_b32_e32 v5, 0xffff0000, v89
	v_mov_b32_e32 v12, v2
	v_mov_b32_e32 v13, v6
	v_pk_fma_f32 v[0:1], v[12:13], v[4:5], v[0:1]
	v_lshlrev_b32_e32 v4, 16, v93
	v_and_b32_e32 v5, 0xffff0000, v93
	v_mov_b32_e32 v6, v3
	v_pk_fma_f32 v[12:13], v[6:7], v[4:5], v[0:1]
	v_rcp_f32_e32 v11, v11
	v_mul_f32_e32 v0, 0xbfb8aa3b, v12
	v_exp_f32_e32 v2, v0
	s_mov_b32 s2, 0x5040100
	v_pk_mul_f32 v[0:1], v[8:9], v[10:11]
	v_mul_f32_e32 v10, 0xbfb8aa3b, v13
	v_add_f32_e32 v16, 1.0, v2
	ds_read_b128 v[2:5], v135 offset:4416
	ds_read_b128 v[6:9], v135 offset:4432
	v_exp_f32_e32 v17, v10
	v_lshlrev_b32_e32 v10, 16, v62
	v_and_b32_e32 v11, 0xffff0000, v62
	s_waitcnt lgkmcnt(1)
	v_mov_b32_e32 v14, v2
	s_waitcnt lgkmcnt(0)
	v_mov_b32_e32 v15, v6
	v_pk_fma_f32 v[10:11], v[14:15], v[10:11], 0 op_sel_hi:[1,1,0]
	v_lshlrev_b32_e32 v14, 16, v82
	v_and_b32_e32 v15, 0xffff0000, v82
	v_mov_b32_e32 v6, v3
	v_pk_fma_f32 v[2:3], v[6:7], v[14:15], v[10:11]
	v_lshlrev_b32_e32 v6, 16, v90
	v_and_b32_e32 v7, 0xffff0000, v90
	v_mov_b32_e32 v10, v4
	v_mov_b32_e32 v11, v8
	v_pk_fma_f32 v[2:3], v[10:11], v[6:7], v[2:3]
	v_lshlrev_b32_e32 v6, 16, v94
	v_and_b32_e32 v7, 0xffff0000, v94
	v_mov_b32_e32 v8, v5
	v_pk_fma_f32 v[10:11], v[8:9], v[6:7], v[2:3]
	v_add_f32_e32 v3, 1.0, v17
	v_mul_f32_e32 v2, 0xbfb8aa3b, v10
	v_exp_f32_e32 v2, v2
	v_rcp_f32_e32 v15, v3
	v_mul_f32_e32 v3, 0xbfb8aa3b, v11
	v_rcp_f32_e32 v14, v16
	v_add_f32_e32 v2, 1.0, v2
	v_exp_f32_e32 v17, v3
	v_rcp_f32_e32 v16, v2
	ds_read_b128 v[2:5], v135 offset:4448
	ds_read_b128 v[6:9], v135 offset:4464
	v_pk_mul_f32 v[12:13], v[12:13], v[14:15]
	v_add_f32_e32 v17, 1.0, v17
	v_rcp_f32_e32 v17, v17
	s_waitcnt lgkmcnt(1)
	v_mov_b32_e32 v20, v2
	s_waitcnt lgkmcnt(0)
	v_mov_b32_e32 v21, v6
	v_pk_fma_f32 v[18:19], v[20:21], v[18:19], 0 op_sel_hi:[1,1,0]
	v_lshlrev_b32_e32 v20, 16, v83
	v_and_b32_e32 v21, 0xffff0000, v83
	v_mov_b32_e32 v6, v3
	v_pk_fma_f32 v[2:3], v[6:7], v[20:21], v[18:19]
	v_lshlrev_b32_e32 v6, 16, v91
	v_and_b32_e32 v7, 0xffff0000, v91
	v_mov_b32_e32 v18, v4
	v_mov_b32_e32 v19, v8
	v_pk_fma_f32 v[2:3], v[18:19], v[6:7], v[2:3]
	v_lshlrev_b32_e32 v6, 16, v95
	v_and_b32_e32 v7, 0xffff0000, v95
	v_mov_b32_e32 v8, v5
	v_pk_fma_f32 v[18:19], v[8:9], v[6:7], v[2:3]
	v_pk_mul_f32 v[10:11], v[10:11], v[16:17]
	v_mul_f32_e32 v2, 0xbfb8aa3b, v18
	v_exp_f32_e32 v2, v2
	v_mul_f32_e32 v3, 0xbfb8aa3b, v19
	v_exp_f32_e32 v3, v3
	v_and_b32_e32 v17, 0xffff0000, v53
	v_add_f32_e32 v2, 1.0, v2
	v_rcp_f32_e32 v20, v2
	v_add_f32_e32 v21, 1.0, v3
	ds_read_b128 v[2:5], v135 offset:4480
	ds_read_b128 v[6:9], v135 offset:4496
	v_rcp_f32_e32 v21, v21
	v_cvt_pk_bf16_f32 v0, v0, v1
	v_cndmask_b32_e64 v1, 0, v0, s[50:51]
	s_waitcnt lgkmcnt(1)
	v_mov_b32_e32 v24, v2
	s_waitcnt lgkmcnt(0)
	v_mov_b32_e32 v25, v6
	v_pk_fma_f32 v[22:23], v[24:25], v[22:23], 0 op_sel_hi:[1,1,0]
	v_lshlrev_b32_e32 v24, 16, v48
	v_and_b32_e32 v25, 0xffff0000, v48
	v_mov_b32_e32 v6, v3
	v_pk_fma_f32 v[2:3], v[6:7], v[24:25], v[22:23]
	v_lshlrev_b32_e32 v6, 16, v84
	v_and_b32_e32 v7, 0xffff0000, v84
	v_mov_b32_e32 v22, v4
	v_mov_b32_e32 v23, v8
	v_pk_fma_f32 v[2:3], v[22:23], v[6:7], v[2:3]
	v_lshlrev_b32_e32 v6, 16, v76
	v_and_b32_e32 v7, 0xffff0000, v76
	v_mov_b32_e32 v8, v5
	v_pk_fma_f32 v[22:23], v[8:9], v[6:7], v[2:3]
	v_pk_mul_f32 v[14:15], v[18:19], v[20:21]
	v_mul_f32_e32 v2, 0xbfb8aa3b, v22
	v_exp_f32_e32 v2, v2
	v_mul_f32_e32 v16, 0xbfb8aa3b, v23
	v_exp_f32_e32 v21, v16
	v_lshlrev_b32_e32 v16, 16, v53
	v_add_f32_e32 v20, 1.0, v2
	ds_read_b128 v[2:5], v135 offset:4512
	ds_read_b128 v[6:9], v135 offset:4528
	v_cndmask_b32_sdwa v0, v193, v0, vcc dst_sel:DWORD dst_unused:UNUSED_PAD src0_sel:DWORD src1_sel:WORD_1
	v_perm_b32 v0, v0, v1, s2
	v_cvt_pk_bf16_f32 v1, v12, v13
	s_waitcnt lgkmcnt(1)
; __device__ __forceinline__ unsigned cvt_pk_bf16(float lo, float hi) { const f32x2 v = {lo, hi}; const bf16v2_t b = __builtin_convertvector(v, bf16v2_t); return __builtin_bit_cast(unsigned, b); }
; __device__ __forceinline__ float bflo(unsigned w) { return __uint_as_float(w << 16); }
; __device__ __forceinline__ float bfhi(unsigned w) { return __uint_as_float(w & 0xffff0000u); }
; __device__ __forceinline__ float siluf_(float x) { return x * __builtin_amdgcn_rcpf(1.0f + __builtin_amdgcn_exp2f(x * -1.44269504089f)); }
; __device__ __forceinline__ void d1_unit(const Params& p, int g, int l, int unit0, int nd1, unsigned char* lds0, const int tidx) {
;     ...
;           for (int i = 0; i < 16; ++i) {
;               const f32x4 w = sCW[X * 128 + d0 + i];
;               float acc = 0.f;
; #pragma unroll
;               for (int j = 0; j < 4; ++j) { const unsigned wd = raw[X][j][i >> 3][(i >> 1) & 3]; acc += ((i & 1) ? bfhi(wd) : bflo(wd)) * w[j]; }
;               y[i] = c < nvalid ? siluf_(acc) : 0.f;
;           }
;           if (X < 2) {
;               float ss = 0.f;
; #pragma unroll
;               for (int i = 0; i < 16; ++i) ss += y[i] * y[i];
;               ss += __shfl_xor(ss, 1); ss += __shfl_xor(ss, 2); ss += __shfl_xor(ss, 4);
;               const float sc = rsqrtf(ss + EPS) * (X == 0 ? 0.08838834764831845f : 1.0f);
; #pragma unroll
;               for (int i = 0; i < 16; ++i) y[i] *= sc;
;           }
;           bf16_t* dst = (X == 0 ? sq : (X == 1 ? sk : sv)) + c * 136 + d0;
;           u32x4 w0, w1;
;           w0.x = cvt_pk_bf16(y[0], y[1]); w0.y = cvt_pk_bf16(y[2], y[3]); w0.z = cvt_pk_bf16(y[4], y[5]); w0.w = cvt_pk_bf16(y[6], y[7]);
;           w1.x = cvt_pk_bf16(y[8], y[9]); w1.y = cvt_pk_bf16(y[10], y[11]); w1.z = cvt_pk_bf16(y[12], y[13]); w1.w = cvt_pk_bf16(y[14], y[15]);
;           *(u32x4*)dst = w0; *(u32x4*)(dst + 8) = w1;
	v_mov_b32_e32 v18, v2
	s_waitcnt lgkmcnt(0)
	v_mov_b32_e32 v19, v6
	v_pk_fma_f32 v[16:17], v[18:19], v[16:17], 0 op_sel_hi:[1,1,0]
	v_lshlrev_b32_e32 v18, 16, v49
	v_and_b32_e32 v19, 0xffff0000, v49
	v_mov_b32_e32 v6, v3
	v_pk_fma_f32 v[2:3], v[6:7], v[18:19], v[16:17]
	v_lshlrev_b32_e32 v6, 16, v85
	v_and_b32_e32 v7, 0xffff0000, v85
	v_mov_b32_e32 v16, v4
	v_mov_b32_e32 v17, v8
	v_pk_fma_f32 v[2:3], v[16:17], v[6:7], v[2:3]
	v_lshlrev_b32_e32 v6, 16, v77
	v_and_b32_e32 v7, 0xffff0000, v77
	v_mov_b32_e32 v8, v5
	v_pk_fma_f32 v[16:17], v[8:9], v[6:7], v[2:3]
	v_add_f32_e32 v3, 1.0, v21
	v_mul_f32_e32 v2, 0xbfb8aa3b, v16
	v_exp_f32_e32 v2, v2
	v_rcp_f32_e32 v19, v3
	v_rcp_f32_e32 v18, v20
	v_mul_f32_e32 v20, 0xbfb8aa3b, v17
	v_add_f32_e32 v26, 1.0, v2
	ds_read_b128 v[2:5], v135 offset:4544
	ds_read_b128 v[6:9], v135 offset:4560
	v_exp_f32_e32 v27, v20
	v_lshlrev_b32_e32 v20, 16, v54
	v_and_b32_e32 v21, 0xffff0000, v54
	s_waitcnt lgkmcnt(1)
	v_mov_b32_e32 v24, v2
	s_waitcnt lgkmcnt(0)
	v_mov_b32_e32 v25, v6
	v_pk_fma_f32 v[20:21], v[24:25], v[20:21], 0 op_sel_hi:[1,1,0]
	v_lshlrev_b32_e32 v24, 16, v50
	v_and_b32_e32 v25, 0xffff0000, v50
	v_mov_b32_e32 v6, v3
	v_pk_fma_f32 v[2:3], v[6:7], v[24:25], v[20:21]
	v_lshlrev_b32_e32 v6, 16, v86
	v_and_b32_e32 v7, 0xffff0000, v86
	v_mov_b32_e32 v20, v4
	v_mov_b32_e32 v21, v8
	v_pk_fma_f32 v[2:3], v[20:21], v[6:7], v[2:3]
	v_lshlrev_b32_e32 v6, 16, v78
	v_and_b32_e32 v7, 0xffff0000, v78
	v_mov_b32_e32 v8, v5
	v_pk_fma_f32 v[20:21], v[8:9], v[6:7], v[2:3]
	v_add_f32_e32 v3, 1.0, v27
	v_mul_f32_e32 v2, 0xbfb8aa3b, v20
	v_exp_f32_e32 v2, v2
	v_rcp_f32_e32 v25, v3
	v_mul_f32_e32 v3, 0xbfb8aa3b, v21
	v_rcp_f32_e32 v24, v26
	v_add_f32_e32 v2, 1.0, v2
	v_exp_f32_e32 v27, v3
	v_rcp_f32_e32 v26, v2
	ds_read_b128 v[2:5], v135 offset:4576
	ds_read_b128 v[6:9], v135 offset:4592
	v_add_f32_e32 v27, 1.0, v27
	v_rcp_f32_e32 v27, v27
	s_waitcnt lgkmcnt(1)
	v_mov_b32_e32 v30, v2
	s_waitcnt lgkmcnt(0)
	v_mov_b32_e32 v31, v6
	v_pk_fma_f32 v[28:29], v[30:31], v[28:29], 0 op_sel_hi:[1,1,0]
	v_lshlrev_b32_e32 v30, 16, v51
	v_and_b32_e32 v31, 0xffff0000, v51
	v_mov_b32_e32 v6, v3
	v_pk_fma_f32 v[2:3], v[6:7], v[30:31], v[28:29]
	v_lshlrev_b32_e32 v6, 16, v87
	v_and_b32_e32 v7, 0xffff0000, v87
	v_mov_b32_e32 v28, v4
	v_mov_b32_e32 v29, v8
	v_pk_fma_f32 v[2:3], v[28:29], v[6:7], v[2:3]
	v_lshlrev_b32_e32 v6, 16, v79
	v_and_b32_e32 v7, 0xffff0000, v79
	v_mov_b32_e32 v8, v5
	v_pk_fma_f32 v[2:3], v[8:9], v[6:7], v[2:3]
	v_pk_mul_f32 v[6:7], v[22:23], v[18:19]
	v_mul_f32_e32 v4, 0xbfb8aa3b, v2
	v_mul_f32_e32 v5, 0xbfb8aa3b, v3
	v_exp_f32_e32 v4, v4
	v_exp_f32_e32 v5, v5
	v_pk_mul_f32 v[8:9], v[16:17], v[24:25]
	v_pk_mul_f32 v[16:17], v[20:21], v[26:27]
	v_add_f32_e32 v4, 1.0, v4
	v_add_f32_e32 v5, 1.0, v5
	v_rcp_f32_e32 v4, v4
	v_rcp_f32_e32 v5, v5
	s_nop 0
	v_pk_mul_f32 v[18:19], v[2:3], v[4:5]
	v_cndmask_b32_e64 v2, 0, v1, s[50:51]
	v_cndmask_b32_sdwa v1, v193, v1, vcc dst_sel:DWORD dst_unused:UNUSED_PAD src0_sel:DWORD src1_sel:WORD_1
	v_perm_b32 v1, v1, v2, s2
	v_cvt_pk_bf16_f32 v2, v10, v11
	v_cndmask_b32_e64 v3, 0, v2, s[50:51]
	v_cndmask_b32_sdwa v2, v193, v2, vcc dst_sel:DWORD dst_unused:UNUSED_PAD src0_sel:DWORD src1_sel:WORD_1
	v_perm_b32 v2, v2, v3, s2
	v_cvt_pk_bf16_f32 v3, v14, v15
	v_cndmask_b32_e64 v4, 0, v3, s[50:51]
	v_cndmask_b32_sdwa v3, v193, v3, vcc dst_sel:DWORD dst_unused:UNUSED_PAD src0_sel:DWORD src1_sel:WORD_1
	v_perm_b32 v3, v3, v4, s2
	v_cvt_pk_bf16_f32 v4, v6, v7
	v_cndmask_b32_e64 v5, 0, v4, s[50:51]
	v_cndmask_b32_sdwa v4, v193, v4, vcc dst_sel:DWORD dst_unused:UNUSED_PAD src0_sel:DWORD src1_sel:WORD_1
	v_perm_b32 v4, v4, v5, s2
	v_cvt_pk_bf16_f32 v5, v8, v9
	v_cndmask_b32_e64 v6, 0, v5, s[50:51]
	v_cndmask_b32_sdwa v5, v193, v5, vcc dst_sel:DWORD dst_unused:UNUSED_PAD src0_sel:DWORD src1_sel:WORD_1
	v_perm_b32 v5, v5, v6, s2
	v_cvt_pk_bf16_f32 v6, v16, v17
	v_cndmask_b32_e64 v7, 0, v6, s[50:51]
	v_cndmask_b32_sdwa v6, v193, v6, vcc dst_sel:DWORD dst_unused:UNUSED_PAD src0_sel:DWORD src1_sel:WORD_1
	v_perm_b32 v6, v6, v7, s2
	v_cvt_pk_bf16_f32 v7, v18, v19
	v_cndmask_b32_e64 v8, 0, v7, s[50:51]
	v_cndmask_b32_sdwa v7, v193, v7, vcc dst_sel:DWORD dst_unused:UNUSED_PAD src0_sel:DWORD src1_sel:WORD_1
	v_perm_b32 v7, v7, v8, s2
	s_mov_b32 s2, 32
	s_andn2_b64 vcc, exec, s[14:15]
	ds_write_b128 v44, v[0:3] offset:34816
	ds_write_b128 v44, v[4:7] offset:34832
	s_cbranch_vccz .LBB0_341

; __device__ __forceinline__ void d1_unit(const Params& p, int g, int l, int unit0, int nd1, unsigned char* lds0, const int tidx) {
;     ...
;               const int rr = c - 3 + j;
;               raw[X][j][0] = (u32x4){0u, 0u, 0u, 0u}; raw[X][j][1] = raw[X][j][0];
;               if (c < nvalid) {
;                   if (rr >= 0) { const bf16_t* src = buf + (size_t)(row0 + rr) * 1024 + 128 * h + d0; raw[X][j][0] = *(const u32x4*)src; raw[X][j][1] = *(const u32x4*)(src + 8); }
.LBB0_242:
	v_add_u32_e32 v0, s60, v49
	v_ashrrev_i32_e32 v1, 31, v0
	v_lshlrev_b64 v[0:1], 11, v[0:1]
	v_lshl_add_u64 v[0:1], v[144:145], 0, v[0:1]
	global_load_dwordx4 v[8:11], v[0:1], off offset:16
	s_nop 0
	global_load_dwordx4 v[0:3], v[0:1], off

; __device__ __forceinline__ void d1_unit(const Params& p, int g, int l, int unit0, int nd1, unsigned char* lds0, const int tidx) {
;     ...
;               const int rr = c - 3 + j;
;               raw[X][j][0] = (u32x4){0u, 0u, 0u, 0u}; raw[X][j][1] = raw[X][j][0];
;               if (c < nvalid) {
;                   if (rr >= 0) { const bf16_t* src = buf + (size_t)(row0 + rr) * 1024 + 128 * h + d0; raw[X][j][0] = *(const u32x4*)src; raw[X][j][1] = *(const u32x4*)(src + 8); }
.LBB0_252:
	v_add_u32_e32 v4, s60, v76
	v_ashrrev_i32_e32 v5, 31, v4
	v_lshlrev_b64 v[4:5], 11, v[4:5]
	v_lshl_add_u64 v[12:13], v[144:145], 0, v[4:5]
	global_load_dwordx4 v[4:7], v[12:13], off offset:16
	s_nop 0
	global_load_dwordx4 v[12:15], v[12:13], off

; __device__ __forceinline__ void d1_unit(const Params& p, int g, int l, int unit0, int nd1, unsigned char* lds0, const int tidx) {
;     ...
;               const int rr = c - 3 + j;
;               raw[X][j][0] = (u32x4){0u, 0u, 0u, 0u}; raw[X][j][1] = raw[X][j][0];
;               if (c < nvalid) {
;                   if (rr >= 0) { const bf16_t* src = buf + (size_t)(row0 + rr) * 1024 + 128 * h + d0; raw[X][j][0] = *(const u32x4*)src; raw[X][j][1] = *(const u32x4*)(src + 8); }
.LBB0_277:
	v_add_u32_e32 v16, s60, v49
	v_ashrrev_i32_e32 v17, 31, v16
	v_lshlrev_b64 v[16:17], 11, v[16:17]
	v_lshl_add_u64 v[16:17], v[150:151], 0, v[16:17]
	global_load_dwordx4 v[28:31], v[16:17], off offset:16
	s_nop 0
	global_load_dwordx4 v[16:19], v[16:17], off

; __device__ __forceinline__ void d1_unit(const Params& p, int g, int l, int unit0, int nd1, unsigned char* lds0, const int tidx) {
;     ...
;               const int rr = c - 3 + j;
;               raw[X][j][0] = (u32x4){0u, 0u, 0u, 0u}; raw[X][j][1] = raw[X][j][0];
;               if (c < nvalid) {
;                   if (rr >= 0) { const bf16_t* src = buf + (size_t)(row0 + rr) * 1024 + 128 * h + d0; raw[X][j][0] = *(const u32x4*)src; raw[X][j][1] = *(const u32x4*)(src + 8); }
.LBB0_287:
	v_add_u32_e32 v20, s60, v76
	v_ashrrev_i32_e32 v21, 31, v20
	v_lshlrev_b64 v[20:21], 11, v[20:21]
	v_lshl_add_u64 v[32:33], v[150:151], 0, v[20:21]
	global_load_dwordx4 v[20:23], v[32:33], off offset:16
	s_nop 0
	global_load_dwordx4 v[32:35], v[32:33], off

; __device__ __forceinline__ void d1_unit(const Params& p, int g, int l, int unit0, int nd1, unsigned char* lds0, const int tidx) {
;     ...
;               const int rr = c - 3 + j;
;               raw[X][j][0] = (u32x4){0u, 0u, 0u, 0u}; raw[X][j][1] = raw[X][j][0];
;               if (c < nvalid) {
;                   if (rr >= 0) { const bf16_t* src = buf + (size_t)(row0 + rr) * 1024 + 128 * h + d0; raw[X][j][0] = *(const u32x4*)src; raw[X][j][1] = *(const u32x4*)(src + 8); }
.LBB0_324:
	v_add_u32_e32 v48, s60, v76
	v_ashrrev_i32_e32 v49, 31, v48
	v_lshlrev_b64 v[48:49], 11, v[48:49]
	v_lshl_add_u64 v[78:79], v[158:159], 0, v[48:49]
	global_load_dwordx4 v[48:51], v[78:79], off offset:16
	global_load_dwordx4 v[80:83], v[78:79], off

; __device__ __forceinline__ unsigned cvt_pk_bf16(float lo, float hi) { const f32x2 v = {lo, hi}; const bf16v2_t b = __builtin_convertvector(v, bf16v2_t); return __builtin_bit_cast(unsigned, b); }
;     __device__ __forceinline__ void res(const f32x4 (&acc)[2][2][4][2], const pg8::Unit& u, int wr, int wc, int fr, int fq) const {
;     ...
;                 for (int bj = 0; bj < 2; ++bj)
; #pragma unroll
;                     for (int n = 0; n < 2; ++n) {
;                         const f32x4 x = xin[m][bj][n] + acc[ai][bj][m][n];
;                         if (ok) {
;                             *(f32x4*)(yp + bj * 128 + n * 16) = x;
;                             if (wxb) { u32x2 w; w.x = cvt_pk_bf16(x[0], x[1]); w.y = cvt_pk_bf16(x[2], x[3]); *(u32x2*)(xp + bj * 128 + n * 16) = w; }
.LBB0_786:
	v_pk_add_f32 v[170:171], v[126:127], v[174:175]
	v_pk_add_f32 v[168:169], v[124:125], v[172:173]
	s_and_b64 vcc, exec, s[44:45]
	global_store_dwordx4 v[232:233], v[168:171], off offset:512
	s_cbranch_vccnz .LBB0_788
	v_cvt_pk_bf16_f32 v172, v168, v169
	v_cvt_pk_bf16_f32 v173, v170, v171
	global_store_dwordx2 v[218:219], v[172:173], off offset:256

; __device__ __forceinline__ unsigned cvt_pk_bf16(float lo, float hi) { const f32x2 v = {lo, hi}; const bf16v2_t b = __builtin_convertvector(v, bf16v2_t); return __builtin_bit_cast(unsigned, b); }
;     __device__ __forceinline__ void res(const f32x4 (&acc)[2][2][4][2], const pg8::Unit& u, int wr, int wc, int fr, int fq) const {
;     ...
;                 for (int bj = 0; bj < 2; ++bj)
; #pragma unroll
;                     for (int n = 0; n < 2; ++n) {
;                         const f32x4 x = xin[m][bj][n] + acc[ai][bj][m][n];
;                         if (ok) {
;                             *(f32x4*)(yp + bj * 128 + n * 16) = x;
;                             if (wxb) { u32x2 w; w.x = cvt_pk_bf16(x[0], x[1]); w.y = cvt_pk_bf16(x[2], x[3]); *(u32x2*)(xp + bj * 128 + n * 16) = w; }
.LBB0_793:
	v_pk_add_f32 v[170:171], v[114:115], v[170:171]
	v_pk_add_f32 v[168:169], v[112:113], v[168:169]
	s_and_b64 vcc, exec, s[44:45]
	global_store_dwordx4 v[232:233], v[168:171], off offset:64
	s_cbranch_vccnz .LBB0_795
	v_cvt_pk_bf16_f32 v188, v168, v169
	v_cvt_pk_bf16_f32 v189, v170, v171
	global_store_dwordx2 v[218:219], v[188:189], off offset:32

; __device__ __forceinline__ unsigned cvt_pk_bf16(float lo, float hi) { const f32x2 v = {lo, hi}; const bf16v2_t b = __builtin_convertvector(v, bf16v2_t); return __builtin_bit_cast(unsigned, b); }
;     __device__ __forceinline__ void res(const f32x4 (&acc)[2][2][4][2], const pg8::Unit& u, int wr, int wc, int fr, int fq) const {
;     ...
;                 for (int bj = 0; bj < 2; ++bj)
; #pragma unroll
;                     for (int n = 0; n < 2; ++n) {
;                         const f32x4 x = xin[m][bj][n] + acc[ai][bj][m][n];
;                         if (ok) {
;                             *(f32x4*)(yp + bj * 128 + n * 16) = x;
;                             if (wxb) { u32x2 w; w.x = cvt_pk_bf16(x[0], x[1]); w.y = cvt_pk_bf16(x[2], x[3]); *(u32x2*)(xp + bj * 128 + n * 16) = w; }
.LBB0_797:
	v_pk_add_f32 v[142:143], v[122:123], v[142:143]
	v_pk_add_f32 v[140:141], v[120:121], v[140:141]
	s_and_b64 vcc, exec, s[44:45]
	global_store_dwordx4 v[232:233], v[140:143], off offset:576
	s_cbranch_vccnz .LBB0_799
	v_cvt_pk_bf16_f32 v168, v140, v141
	v_cvt_pk_bf16_f32 v169, v142, v143
	global_store_dwordx2 v[218:219], v[168:169], off offset:288

;     __device__ __forceinline__ void res(const f32x4 (&acc)[2][2][4][2], const pg8::Unit& u, int wr, int wc, int fr, int fq) const {
;     ...
;                 ss += __shfl_xor(ss, 16); ss += __shfl_xor(ss, 32);
;                 if (ok && fq == 0) atomicAdd(rs_out + r, ss);
.LBB0_800:
	s_or_b64 exec, exec, s[14:15]
	v_and_b32_e32 v141, 64, v244
	v_xor_b32_e32 v140, 16, v244
	v_add_u32_e32 v141, 64, v141
	v_cmp_lt_i32_e32 vcc, v140, v141
	v_xor_b32_e32 v142, 32, v244
	v_readlane_b32 s0, v254, 56
	v_cndmask_b32_e32 v140, v244, v140, vcc
	v_lshlrev_b32_e32 v195, 2, v140
	ds_bpermute_b32 v140, v195, v192
	v_cmp_lt_i32_e32 vcc, v142, v141
	v_readlane_b32 s1, v254, 57
	s_and_b64 s[8:9], s[38:39], s[8:9]
	v_cndmask_b32_e32 v141, v244, v142, vcc
	v_lshlrev_b32_e32 v211, 2, v141
	s_waitcnt lgkmcnt(0)
	v_add_f32_e32 v140, v192, v140
	ds_bpermute_b32 v141, v211, v140
	v_lshl_add_u64 v[218:219], v[214:215], 2, s[0:1]
	s_and_saveexec_b64 s[0:1], s[8:9]
	s_cbranch_execz .LBB0_802
	s_waitcnt lgkmcnt(0)
	v_add_f32_e32 v140, v140, v141
	global_atomic_add_f32 v[218:219], v140, off

; __device__ __forceinline__ unsigned cvt_pk_bf16(float lo, float hi) { const f32x2 v = {lo, hi}; const bf16v2_t b = __builtin_convertvector(v, bf16v2_t); return __builtin_bit_cast(unsigned, b); }
;     __device__ __forceinline__ void res(const f32x4 (&acc)[2][2][4][2], const pg8::Unit& u, int wr, int wc, int fr, int fq) const {
;     ...
;                 for (int bj = 0; bj < 2; ++bj)
; #pragma unroll
;                     for (int n = 0; n < 2; ++n) {
;                         const f32x4 x = xin[m][bj][n] + acc[ai][bj][m][n];
;                         if (ok) {
;                             *(f32x4*)(yp + bj * 128 + n * 16) = x;
;                             if (wxb) { u32x2 w; w.x = cvt_pk_bf16(x[0], x[1]); w.y = cvt_pk_bf16(x[2], x[3]); *(u32x2*)(xp + bj * 128 + n * 16) = w; }
.LBB0_925:
	v_pk_add_f32 v[146:147], v[62:63], v[150:151]
	v_pk_add_f32 v[144:145], v[60:61], v[148:149]
	s_and_b64 vcc, exec, s[44:45]
	global_store_dwordx4 v[228:229], v[144:147], off offset:512
	s_cbranch_vccnz .LBB0_927
	v_cvt_pk_bf16_f32 v148, v144, v145
	v_cvt_pk_bf16_f32 v149, v146, v147
	global_store_dwordx2 v[220:221], v[148:149], off offset:256

; __device__ __forceinline__ unsigned cvt_pk_bf16(float lo, float hi) { const f32x2 v = {lo, hi}; const bf16v2_t b = __builtin_convertvector(v, bf16v2_t); return __builtin_bit_cast(unsigned, b); }
;     __device__ __forceinline__ void res(const f32x4 (&acc)[2][2][4][2], const pg8::Unit& u, int wr, int wc, int fr, int fq) const {
;     ...
;                 for (int bj = 0; bj < 2; ++bj)
; #pragma unroll
;                     for (int n = 0; n < 2; ++n) {
;                         const f32x4 x = xin[m][bj][n] + acc[ai][bj][m][n];
;                         if (ok) {
;                             *(f32x4*)(yp + bj * 128 + n * 16) = x;
;                             if (wxb) { u32x2 w; w.x = cvt_pk_bf16(x[0], x[1]); w.y = cvt_pk_bf16(x[2], x[3]); *(u32x2*)(xp + bj * 128 + n * 16) = w; }
.LBB0_929:
	v_pk_add_f32 v[146:147], v[50:51], v[146:147]
	v_pk_add_f32 v[144:145], v[48:49], v[144:145]
	s_and_b64 vcc, exec, s[44:45]
	global_store_dwordx4 v[228:229], v[144:147], off offset:64
	s_cbranch_vccnz .LBB0_931
	v_cvt_pk_bf16_f32 v176, v144, v145
	v_cvt_pk_bf16_f32 v177, v146, v147
	global_store_dwordx2 v[220:221], v[176:177], off offset:32

; __device__ __forceinline__ unsigned cvt_pk_bf16(float lo, float hi) { const f32x2 v = {lo, hi}; const bf16v2_t b = __builtin_convertvector(v, bf16v2_t); return __builtin_bit_cast(unsigned, b); }
;     __device__ __forceinline__ void res(const f32x4 (&acc)[2][2][4][2], const pg8::Unit& u, int wr, int wc, int fr, int fq) const {
;     ...
;                 for (int bj = 0; bj < 2; ++bj)
; #pragma unroll
;                     for (int n = 0; n < 2; ++n) {
;                         const f32x4 x = xin[m][bj][n] + acc[ai][bj][m][n];
;                         if (ok) {
;                             *(f32x4*)(yp + bj * 128 + n * 16) = x;
;                             if (wxb) { u32x2 w; w.x = cvt_pk_bf16(x[0], x[1]); w.y = cvt_pk_bf16(x[2], x[3]); *(u32x2*)(xp + bj * 128 + n * 16) = w; }
.LBB0_933:
	v_pk_add_f32 v[130:131], v[58:59], v[130:131]
	v_pk_add_f32 v[128:129], v[56:57], v[128:129]
	s_and_b64 vcc, exec, s[44:45]
	global_store_dwordx4 v[228:229], v[128:131], off offset:576
	s_cbranch_vccnz .LBB0_935
	v_cvt_pk_bf16_f32 v144, v128, v129
	v_cvt_pk_bf16_f32 v145, v130, v131
	global_store_dwordx2 v[220:221], v[144:145], off offset:288

;     __device__ __forceinline__ void res(const f32x4 (&acc)[2][2][4][2], const pg8::Unit& u, int wr, int wc, int fr, int fq) const {
;     ...
;                 ss += __shfl_xor(ss, 16); ss += __shfl_xor(ss, 32);
;                 if (ok && fq == 0) atomicAdd(rs_out + r, ss);
.LBB0_936:
	s_or_b64 exec, exec, s[14:15]
	ds_bpermute_b32 v128, v195, v192
	s_and_b64 s[8:9], s[38:39], s[8:9]
	s_waitcnt lgkmcnt(0)
	v_add_f32_e32 v128, v192, v128
	ds_bpermute_b32 v129, v211, v128
	s_and_saveexec_b64 s[0:1], s[8:9]
	s_cbranch_execz .LBB0_938
	s_waitcnt lgkmcnt(0)
	v_add_f32_e32 v128, v128, v129
	global_atomic_add_f32 v[218:219], v128, off offset:512
